# NA band step: bias masking by per-lane constant addends (valid ? 0 : -inf, computed once per phase) and a -inf bias row for lanes outside the band, instead of 16 x (add, compare, select) per step
# speedup vs baseline: 1.0077x; 1.0077x over previous
.LBB0_1064:
	s_cmp_gt_i32 s52, 10
	s_cselect_b64 s[0:1], -1, 0
	s_cmp_lt_i32 s53, 11
	s_cselect_b64 s[2:3], -1, 0
	s_or_b64 s[0:1], s[0:1], s[2:3]
	s_and_b64 vcc, exec, s[0:1]
	s_cbranch_vccnz .LBB0_1182
	s_cmpk_gt_i32 s10, 0x7ff
	s_cbranch_scc1 .LBB0_1130
	v_readlane_b32 s13, v239, 43
	s_lshr_b32 s1, s13, 7
	v_mbcnt_lo_u32_b32 v0, -1, 0
	s_and_b32 s11, s1, 0x1fffffe
	s_lshl_b32 s1, s62, 4
	v_mbcnt_hi_u32_b32 v1, -1, v0
	s_and_b32 s1, s1, 48
	v_and_b32_e32 v6, 15, v1
	v_med3_u32 v7, s1, 8, 40
	v_or_b32_e32 v2, s1, v6
	v_and_b32_e32 v4, 7, v1
	v_add_u32_e32 v10, -8, v7
	s_waitcnt lgkmcnt(1)
	v_lshrrev_b32_e32 v5, 5, v1
	v_or_b32_e32 v109, 0x100, v2
	v_med3_u32 v8, v2, 8, 56
	v_lshlrev_b32_e32 v2, 3, v4
	v_lshlrev_b32_e32 v94, 4, v4
	v_add_u16_e32 v4, v1, v10
	v_lshrrev_b16_e32 v12, 1, v4
	v_lshlrev_b32_e32 v4, 2, v5
	v_add_u32_e32 v13, v4, v7
	v_sub_u32_e32 v115, v13, v8
	v_bitop3_b32 v8, v12, v5, 7 bitop3:0x6c
	s_and_b32 s0, s13, 0xffffffc0
	v_and_b32_e32 v3, 31, v1
	v_lshlrev_b32_e32 v117, 4, v8
	v_add_u32_e32 v8, 2, v5
	v_add_u32_e32 v90, s0, v1
	v_lshlrev_b32_e32 v9, 4, v1
	s_movk_i32 s0, 0x70
	v_add_lshl_u32 v114, v3, v10, 7
	v_lshlrev_b32_e32 v116, 1, v10
	v_bitop3_b32 v10, v12, v8, 7 bitop3:0x6c
	v_bitop3_b32 v112, v90, s0, v9 bitop3:0x48
	v_lshrrev_b32_e32 v9, 1, v1
	v_lshlrev_b32_e32 v118, 4, v10
	v_or_b32_e32 v10, 4, v5
	s_waitcnt lgkmcnt(0)
	v_bfe_u32 v11, v1, 1, 3
	v_bitop3_b32 v10, v12, v10, 7 bitop3:0x6c
	v_bitop3_b32 v8, v8, v9, 7 bitop3:0x78
	v_lshlrev_b32_e32 v119, 4, v10
	v_add_u32_e32 v10, 6, v5
	v_lshlrev_b32_e32 v122, 4, v8
	v_bitop3_b32 v8, v5, v11, 4 bitop3:0x36
	v_lshlrev_b32_e32 v123, 4, v8
	v_bitop3_b32 v8, v10, v9, 7 bitop3:0x78
	v_lshlrev_b32_e32 v124, 4, v8
	v_max_i32_e32 v8, 0xffffffd1, v90
	v_sub_u32_e32 v8, v8, v90
	v_bitop3_b32 v12, v12, v10, 7 bitop3:0x6c
	v_add_u32_e32 v8, 0x1ff, v8
	v_lshlrev_b32_e32 v120, 4, v12
	v_bitop3_b32 v12, v9, v5, 7 bitop3:0x6c
	v_lshrrev_b32_e32 v9, 9, v8
	v_bfe_u32 v108, v1, 4, 1
	v_add_u32_e32 v10, 1, v9
	v_add_u32_e32 v9, -1, v9
	v_lshlrev_b32_e32 v1, 2, v1
	v_lshrrev_b32_e32 v11, 1, v9
	v_lshl_add_u32 v1, s62, 8, v1
	v_add_u32_e32 v126, 0x21100, v1
	v_add_u16_e32 v1, 1, v11
	v_lshlrev_b32_e32 v0, 3, v5
	s_movk_i32 s12, 0x88
	v_and_b32_e32 v128, 7, v1
	v_lshlrev_b32_e32 v1, 2, v7
	v_ashrrev_i32_e32 v92, 3, v90
	v_lshlrev_b32_e32 v113, 7, v3
	v_mad_u32_u24 v125, v3, s12, v0
	v_lshl_add_u32 v1, v5, 4, v1
	v_lshlrev_b32_e32 v3, 2, v6
	v_mul_lo_u32 v110, v92, s12
	v_sub_u32_e32 v1, v1, v3
	s_and_b32 s12, s13, 0xc0
	v_subrev_u32_e32 v1, s12, v1
	v_mul_u32_u24_e32 v3, 0x7c, v108
	s_lshr_b32 s12, s13, 8
	v_mov_b32_e32 v89, 0
	v_lshlrev_b32_e32 v121, 4, v12
	v_readlane_b32 s36, v239, 32
	s_movk_i32 s2, 0x1ff
	v_add_u32_e32 v12, 1, v11
	v_sub_u32_e32 v1, v1, v3
	s_mulk_i32 s12, 0xf8
	s_movk_i32 s0, 0x1d1
	v_mov_b32_e32 v95, v89
	v_readlane_b32 s37, v239, 33
	v_readlane_b32 s42, v239, 38
	v_readlane_b32 s43, v239, 39
	v_cmp_lt_u32_e64 s[2:3], s2, v8
	v_and_b32_e32 v8, 0xfffffe, v10
	v_and_b32_e32 v13, 7, v12
	v_subrev_u32_e32 v1, s12, v1
	s_mov_b32 s23, 0
	v_ashrrev_i32_e32 v93, 31, v92
	v_lshlrev_b32_e32 v111, 7, v92
	v_cmp_gt_i32_e64 s[0:1], s0, v90
	v_lshl_add_u64 v[96:97], s[42:43], 0, v[94:95]
	v_lshl_add_u32 v95, v8, 9, v90
	v_add_u32_e32 v91, 0x200, v90
	v_cmp_lt_u32_e64 s[4:5], 13, v9
	v_cmp_ne_u32_e64 s[6:7], 0, v13
	v_cmp_ne_u32_e64 s[8:9], v10, v8
	v_and_b32_e32 v127, -8, v12
	v_add_u32_e32 v129, 0x21290, v1
	v_mov_b32_e32 v130, 0x900
	v_lshlrev_b32_e32 v98, 1, v0
	v_mov_b32_e32 v99, v89
	v_lshlrev_b32_e32 v100, 1, v2
	v_mov_b32_e32 v101, v89
	s_movk_i32 s33, 0x1200
	s_movk_i32 s34, 0x2000
	s_mov_b64 s[24:25], 0x800
	s_movk_i32 s35, 0xffd0
	s_movk_i32 s36, 0xffef
	s_mov_b32 s37, 0xff800000
	v_lshlrev_b32_e32 v88, 1, v4
	v_mov_b32_e32 v131, 0x21900
	v_mov_b32_e32 v132, 0x21100
	v_mov_b32_e32 v133, 0x3e8
	s_mov_b32 s44, s10
	s_mov_b32 s45, s10
	v_readlane_b32 s38, v239, 34
	v_readlane_b32 s39, v239, 35
	v_readlane_b32 s40, v239, 36
	v_readlane_b32 s41, v239, 37
	v_mov_b32_e32 v214, 0xff800000
	v_mov_b32_e32 v215, 0
	v_cmp_gt_u32_e32 vcc, 16, v115
	v_cndmask_b32_e32 v196, v214, v215, vcc
	v_add_u32_e32 v213, 1, v115
	v_cmp_gt_u32_e32 vcc, 16, v213
	v_cndmask_b32_e32 v197, v214, v215, vcc
	v_add_u32_e32 v213, 2, v115
	v_cmp_gt_u32_e32 vcc, 16, v213
	v_cndmask_b32_e32 v198, v214, v215, vcc
	v_add_u32_e32 v213, 3, v115
	v_cmp_gt_u32_e32 vcc, 16, v213
	v_cndmask_b32_e32 v199, v214, v215, vcc
	v_add_u32_e32 v213, 8, v115
	v_cmp_gt_u32_e32 vcc, 16, v213
	v_cndmask_b32_e32 v200, v214, v215, vcc
	v_add_u32_e32 v213, 9, v115
	v_cmp_gt_u32_e32 vcc, 16, v213
	v_cndmask_b32_e32 v201, v214, v215, vcc
	v_add_u32_e32 v213, 10, v115
	v_cmp_gt_u32_e32 vcc, 16, v213
	v_cndmask_b32_e32 v202, v214, v215, vcc
	v_add_u32_e32 v213, 11, v115
	v_cmp_gt_u32_e32 vcc, 16, v213
	v_cndmask_b32_e32 v203, v214, v215, vcc
	v_add_u32_e32 v213, 16, v115
	v_cmp_gt_u32_e32 vcc, 16, v213
	v_cndmask_b32_e32 v204, v214, v215, vcc
	v_add_u32_e32 v213, 17, v115
	v_cmp_gt_u32_e32 vcc, 16, v213
	v_cndmask_b32_e32 v205, v214, v215, vcc
	v_add_u32_e32 v213, 18, v115
	v_cmp_gt_u32_e32 vcc, 16, v213
	v_cndmask_b32_e32 v206, v214, v215, vcc
	v_add_u32_e32 v213, 19, v115
	v_cmp_gt_u32_e32 vcc, 16, v213
	v_cndmask_b32_e32 v207, v214, v215, vcc
	v_add_u32_e32 v213, 24, v115
	v_cmp_gt_u32_e32 vcc, 16, v213
	v_cndmask_b32_e32 v208, v214, v215, vcc
	v_add_u32_e32 v213, 25, v115
	v_cmp_gt_u32_e32 vcc, 16, v213
	v_cndmask_b32_e32 v209, v214, v215, vcc
	v_add_u32_e32 v213, 26, v115
	v_cmp_gt_u32_e32 vcc, 16, v213
	v_cndmask_b32_e32 v210, v214, v215, vcc
	v_add_u32_e32 v213, 27, v115
	v_cmp_gt_u32_e32 vcc, 16, v213
	v_cndmask_b32_e32 v211, v214, v215, vcc
	v_mbcnt_lo_u32_b32 v213, -1, 0
	v_mbcnt_hi_u32_b32 v213, -1, v213
	v_mov_b32_e32 v212, 0x21880
	v_lshl_add_u32 v213, v213, 2, v212
	ds_write_b32 v213, v214
	s_branch .LBB0_1069

.LBB0_1086:
	s_cmp_gt_u32 s41, 3
	s_mov_b64 s[12:13], -1
	s_cbranch_scc0 .LBB0_1125
	s_add_i32 s41, s22, s41
	s_add_i32 s42, s41, -4
	v_cmp_ge_i32_e32 vcc, s41, v135
	v_cmp_lt_i32_e64 s[12:13], s42, v136
	s_and_b64 s[12:13], vcc, s[12:13]
	s_andn2_b64 vcc, exec, s[12:13]
	v_mov_b32_e32 v144, v139
	v_mov_b32_e32 v141, v140
	s_cbranch_vccnz .LBB0_1123
	v_add_u32_e32 v36, s40, v114
	v_add_u32_e32 v32, v36, v117
	v_add_u32_e32 v37, v36, v118
	ds_read_b128 v[32:35], v32
	ds_read_b128 v[48:51], v37
	v_add_u32_e32 v37, v36, v119
	v_add_u32_e32 v36, v36, v120
	ds_read_b128 v[52:55], v37
	ds_read_b128 v[56:59], v36
	v_cmp_ge_i32_e32 vcc, s41, v134
	v_cmp_lt_i32_e64 s[12:13], s42, v137
	s_and_b64 vcc, vcc, s[12:13]
	v_cndmask_b32_e32 v159, v212, v138, vcc
	ds_read2_b32 v[240:241], v159 offset1:1
	ds_read2_b32 v[242:243], v159 offset0:2 offset1:3
	ds_read2_b32 v[244:245], v159 offset0:8 offset1:9
	ds_read2_b32 v[246:247], v159 offset0:10 offset1:11
	ds_read2_b32 v[248:249], v159 offset0:16 offset1:17
	ds_read2_b32 v[250:251], v159 offset0:18 offset1:19
	ds_read2_b32 v[252:253], v159 offset0:24 offset1:25
	ds_read2_b32 v[254:255], v159 offset0:26 offset1:27
	s_waitcnt lgkmcnt(11)
	v_mfma_f32_32x32x16_bf16 v[32:47], v[32:35], v[64:67], 0
	s_waitcnt lgkmcnt(10)
	v_mfma_f32_32x32x16_bf16 v[32:47], v[48:51], v[68:71], v[32:47]
	s_waitcnt lgkmcnt(9)
	v_mfma_f32_32x32x16_bf16 v[32:47], v[52:55], v[72:75], v[32:47]
	s_waitcnt lgkmcnt(0)
	v_add_f32_e32 v240, v240, v196
	v_add_f32_e32 v241, v241, v197
	v_add_f32_e32 v242, v242, v198
	v_add_f32_e32 v243, v243, v199
	v_add_f32_e32 v244, v244, v200
	v_add_f32_e32 v245, v245, v201
	v_add_f32_e32 v246, v246, v202
	v_add_f32_e32 v247, v247, v203
	v_mfma_f32_32x32x16_bf16 v[32:47], v[56:59], v[76:79], v[32:47]
	v_add_f32_e32 v248, v248, v204
	v_add_f32_e32 v249, v249, v205
	v_add_f32_e32 v250, v250, v206
	v_add_f32_e32 v251, v251, v207
	v_add_f32_e32 v252, v252, v208
	v_add_f32_e32 v253, v253, v209
	v_add_f32_e32 v254, v254, v210
	v_add_f32_e32 v255, v255, v211
	s_nop 4
	v_add_f32_e32 v142, v32, v240
	v_add_f32_e32 v141, v33, v241
	v_add_f32_e32 v145, v34, v242
	v_add_f32_e32 v143, v35, v243
	v_add_f32_e32 v147, v36, v244
	v_add_f32_e32 v146, v37, v245
	v_add_f32_e32 v149, v38, v246
	v_add_f32_e32 v148, v39, v247
	v_add_f32_e32 v151, v40, v248
	v_add_f32_e32 v150, v41, v249
	v_add_f32_e32 v153, v42, v250
	v_add_f32_e32 v152, v43, v251
	v_add_f32_e32 v155, v44, v252
	v_add_f32_e32 v154, v45, v253
	v_add_f32_e32 v157, v46, v254
	v_add_f32_e32 v156, v47, v255
	v_max3_f32 v32, v142, s37, v141
	v_max3_f32 v32, v32, v145, v143
	v_max3_f32 v32, v32, v147, v146
	v_max3_f32 v32, v32, v149, v148
	v_max3_f32 v32, v32, v151, v150
	v_max3_f32 v32, v32, v153, v152
	v_max3_f32 v32, v32, v155, v154
	v_max3_f32 v32, v32, v157, v156
	v_mov_b32_e32 v33, v32
	s_nop 1
	v_permlane32_swap_b32_e32 v32, v33
	v_max_f32_e32 v33, v33, v33
	v_max_f32_e32 v32, v32, v32
	v_max_f32_e32 v159, v32, v33
	v_add_f32_e32 v32, 0x40b00000, v139
	v_cmp_gt_f32_e32 vcc, v159, v32
	v_mov_b32_e32 v158, v140
	v_mov_b32_e32 v144, v139
	s_cbranch_vccz .LBB0_1122
	v_cndmask_b32_e32 v144, v139, v159, vcc
	v_sub_f32_e32 v32, v139, v144
	v_mul_f32_e32 v32, 0x3fb8aa3b, v32
	v_exp_f32_e32 v158, v32
	s_nop 0
	v_pk_mul_f32 v[30:31], v[30:31], v[158:159] op_sel_hi:[1,0]
	v_pk_mul_f32 v[28:29], v[28:29], v[158:159] op_sel_hi:[1,0]
	v_pk_mul_f32 v[26:27], v[26:27], v[158:159] op_sel_hi:[1,0]
	v_pk_mul_f32 v[24:25], v[24:25], v[158:159] op_sel_hi:[1,0]
	v_pk_mul_f32 v[22:23], v[22:23], v[158:159] op_sel_hi:[1,0]
	v_pk_mul_f32 v[20:21], v[20:21], v[158:159] op_sel_hi:[1,0]
	v_pk_mul_f32 v[18:19], v[18:19], v[158:159] op_sel_hi:[1,0]
	v_pk_mul_f32 v[16:17], v[16:17], v[158:159] op_sel_hi:[1,0]
	v_pk_mul_f32 v[14:15], v[14:15], v[158:159] op_sel_hi:[1,0]
	v_pk_mul_f32 v[12:13], v[12:13], v[158:159] op_sel_hi:[1,0]
	v_pk_mul_f32 v[10:11], v[10:11], v[158:159] op_sel_hi:[1,0]
	v_pk_mul_f32 v[8:9], v[8:9], v[158:159] op_sel_hi:[1,0]
	v_pk_mul_f32 v[6:7], v[6:7], v[158:159] op_sel_hi:[1,0]
	v_pk_mul_f32 v[4:5], v[4:5], v[158:159] op_sel_hi:[1,0]
	v_pk_mul_f32 v[2:3], v[2:3], v[158:159] op_sel_hi:[1,0]
	v_pk_mul_f32 v[0:1], v[0:1], v[158:159] op_sel_hi:[1,0]
	v_mul_f32_e32 v158, v140, v158
